# v22: v20 + 12us entry stagger of odd-local-index workgroups within each XCD at G_OUT-GEMM, MLPOUT and PLE
# baseline (speedup 1.0000x reference)
; #define GRID_BAR() xcd_barrier(bar)
; #define GRID_BAR() do {} while (0)
;     __host__ __device__ bool next(int i, Unit& u) const {
;         const long L = (long)i * G + c; if (L >= nwg) return false;
;         int wgid = (int)L; { const int q = nwg / NXCD, r = nwg % NXCD, xcd = wgid % NXCD, off = wgid / NXCD; wgid = (xcd < r ? xcd * (q + 1) : r * (q + 1) + (xcd - r) * q) + off; }
;         const int nig = WGM * nN, gid = wgid / nig, fm = gid * WGM, gsz = (nM - fm) < WGM ? (nM - fm) : WGM;
;         u.pm = fm + ((wgid % nig) % gsz); u.pn = (wgid % nig) / gsz; return true;
; __global__ void __launch_bounds__(NWAVES * 64, 2) mk_fwd(Args args) {
;     ...
;         GRID_BAR();
;         pg8::Gemm g{(const bf16*)(ws + WS_X8C), (const bf16*)(ws + WS_W8O), M, D, D / 2, D / 2, D / 2, 0}; pg8::StaticOrder S; S.init(M, D, F.G, bx);
;         pg8::EpiF<0, true> E{F.in[0], F.out, nullptr, nullptr, XB, (float*)(ws + CTL_SS2), (unsigned*)(ws + CTL_RMAX2), (const float*)(ws + WS_SX3), (const float*)(ws + WS_SWO)};
;         pg8::gemm_phase<pg8::EpiF<0, true>, pg8::StaticOrder, true, true, true>(F.lds + RING_OFF, g, S, E);
.Lstg_gout:
	v_readfirstlane_b32 s98, v0
	s_nop 3
	s_and_b32 s98, s98, 0x3ff
	s_lshr_b32 s98, s98, 6
	s_cmp_ge_u32 s98, 4
	s_cbranch_scc1 .Lprio_gout
	s_setprio 1
.Lprio_gout:
	v_readlane_b32 s0, v254, 3
	v_readlane_b32 s1, v254, 4
	s_mov_b32 s2, s0
	s_cmpk_lt_i32 s0, 0x400
	s_cselect_b64 s[0:1], -1, 0
	s_cmpk_gt_i32 s2, 0x3ff
	v_readfirstlane_b32 s4, v0
	s_waitcnt lgkmcnt(0)
	s_barrier
	s_cbranch_scc1 .LBB0_1708
	v_readlane_b32 s2, v254, 3
	s_mov_b32 s6, s2
	s_ashr_i32 s2, s2, 31
	s_lshr_b32 s2, s2, 29
	s_add_i32 s5, s6, s2
	s_and_b32 s2, s5, -8
	s_sub_i32 s6, s6, s2
	s_cmp_gt_i32 s6, -1
	v_readlane_b32 s3, v254, 4
	s_cbranch_scc0 .LBB0_1705
	s_lshl_b32 s7, s6, 7
	s_cbranch_execz .LBB0_1706
	s_branch .LBB0_1707

;     __host__ __device__ bool next(int i, Unit& u) const {
;         const long L = (long)i * G + c; if (L >= nwg) return false;
;         int wgid = (int)L; { const int q = nwg / NXCD, r = nwg % NXCD, xcd = wgid % NXCD, off = wgid / NXCD; wgid = (xcd < r ? xcd * (q + 1) : r * (q + 1) + (xcd - r) * q) + off; }
;         const int nig = WGM * nN, gid = wgid / nig, fm = gid * WGM, gsz = (nM - fm) < WGM ? (nM - fm) : WGM;
;         u.pm = fm + ((wgid % nig) % gsz); u.pn = (wgid % nig) / gsz; return true;
; __global__ void __launch_bounds__(NWAVES * 64, 2) mk_fwd(Args args) {
;     ...
;         pg8::Gemm g{(const bf16*)(ws + WS_HID), (const bf16*)(ws + WS_WMLPOUT), M, D, DFF, DFF, DFF, 0}; pg8::StaticOrder S; S.init(M, D, F.G, bx);
;         pg8::EpiF<0> E{F.out, F.out, nullptr, nullptr, XB, (float*)(ws + CTL_SS3), (unsigned*)(ws + CTL_RMAX4), nullptr, nullptr};
;         pg8::gemm_phase<pg8::EpiF<0>, pg8::StaticOrder, true, true>(F.lds + RING_OFF, g, S, E);
.Lstg_mlpout:
	v_readfirstlane_b32 s98, v0
	s_nop 3
	s_and_b32 s98, s98, 0x3ff
	s_lshr_b32 s98, s98, 6
	s_cmp_ge_u32 s98, 4
	s_cbranch_scc1 .Lprio_mlpout
	s_setprio 1
.Lprio_mlpout:
	v_readlane_b32 s0, v254, 3
	v_readlane_b32 s1, v254, 4
	s_mov_b32 s2, s0
	s_cmpk_lt_i32 s0, 0x400
	s_cselect_b64 s[0:1], -1, 0
	s_cmpk_gt_i32 s2, 0x3ff
	v_readfirstlane_b32 s4, v0
	s_cbranch_scc1 .LBB0_2079
	v_readlane_b32 s2, v254, 3
	s_mov_b32 s6, s2
	s_ashr_i32 s2, s2, 31
	s_lshr_b32 s2, s2, 29
	s_add_i32 s5, s6, s2
	s_and_b32 s2, s5, -8
	s_sub_i32 s6, s6, s2
	s_cmp_gt_i32 s6, -1
	v_readlane_b32 s3, v254, 4
	s_cbranch_scc0 .LBB0_2163
	s_lshl_b32 s7, s6, 7
	s_cbranch_execz .LBB0_2164
	s_branch .LBB0_2165

;     __host__ __device__ bool next(int i, Unit& u) const {
;         const long L = (long)i * G + c; if (L >= nwg) return false;
;         int wgid = (int)L; { const int q = nwg / NXCD, r = nwg % NXCD, xcd = wgid % NXCD, off = wgid / NXCD; wgid = (xcd < r ? xcd * (q + 1) : r * (q + 1) + (xcd - r) * q) + off; }
;         const int nig = WGM * nN, gid = wgid / nig, fm = gid * WGM, gsz = (nM - fm) < WGM ? (nM - fm) : WGM;
;         u.pm = fm + ((wgid % nig) % gsz); u.pn = (wgid % nig) / gsz; return true;
; template <class Epi, class Sched, bool ALIGN_EPI = false, bool SP2 = false, bool I8 = false>
; __device__ __forceinline__ void gemm_phase(PG8_LAS unsigned char* lds, const Gemm g, const Sched& S, const Epi& E) {
;     const int tid = threadIdx.x, wid = __builtin_amdgcn_readfirstlane(tid >> 6), lane = tid & 63, wr = wid >> 2, wc = wid & 3, fr = lane & 15, fq = lane >> 4;
.Lstg_ple:
	v_readfirstlane_b32 s98, v0
	s_nop 3
	s_and_b32 s98, s98, 0x3ff
	s_lshr_b32 s98, s98, 6
	s_cmp_ge_u32 s98, 4
	s_cbranch_scc1 .Lprio_ple
	s_setprio 1
.Lprio_ple:
	v_readlane_b32 s0, v254, 3
	s_cmpk_gt_i32 s0, 0x3ff
	v_readfirstlane_b32 s16, v0
	v_readlane_b32 s1, v254, 4
	s_cbranch_scc1 .LBB0_2329
	v_readlane_b32 s0, v254, 3
	s_ashr_i32 s33, s0, 31
	s_mov_b32 s2, s0
	s_lshr_b32 s0, s33, 29
	s_add_i32 s4, s2, s0
	s_and_b32 s0, s4, -8
	s_sub_i32 s3, s2, s0
	s_cmp_gt_i32 s3, -1
	v_readlane_b32 s1, v254, 4
	s_cbranch_scc0 .LBB0_2308
	s_lshl_b32 s2, s3, 7
	s_ashr_i32 s0, s4, 3
	s_cbranch_execz .LBB0_2309
	s_branch .LBB0_2310
